# P3 decode compression GEMM: K-tiles i and i+16 per loop iteration (overlapping A rows fetched twice within one iteration instead of eight iterations apart)
# speedup vs baseline: 1.0094x; 1.0094x over previous
;     __device__ __forceinline__ const char* abase(const Gemm& g, const Unit& u) const { return (const char*)g.A + (size_t)u.pm * ((size_t)BM * g.lda * 2); }
; #define PG8_WAIT_V(n) asm volatile("s_waitcnt vmcnt(" #n ")" ::: "memory")
; template <class Epi, class Sched, bool ALIGN_EPI = false, bool SP2 = false>
; __device__ __forceinline__ void gemm_phase(PG8_LAS unsigned char* lds, const Gemm g, const Sched& S, const Epi& E, int wave_sgpr) {
;     ...
;     for (int i = 0; i < 2; ++i) { int R, C; stage_rc(tid * 16 + i * 8192, R, C); const int Rb = Epi::PERM ? ((R & ~31) + perm32(R & 31)) : R;
;         voffA[i] = (unsigned)(R * g.lda + C) * 2u; voffB[i] = (unsigned)(Rb * g.ldb + C) * 2u; }
;     const size_t kstep = (size_t)(BK * 2);
;     const size_t hstepA = (size_t)HALF * g.lda * 2, hstepB = (size_t)HALF * g.ldb * 2;
;     const unsigned ldsw = (unsigned)wid * 1024u;
;     const int aoff = lds_byte(wr * 64 + fr, fq * 8), boff = lds_byte(wc * 32 + fr, fq * 8);
;     ...
;     Unit cur, nxt; int ui = 0;
;     if (!S.next(0, cur)) return;
;     f32x4 acc[2][2][4][2];
; #pragma unroll
;     for (int a = 0; a < 2; ++a)
; #pragma unroll
;         for (int b = 0; b < 2; ++b)
; #pragma unroll
;             for (int m = 0; m < 4; ++m)
; #pragma unroll
;                 for (int n = 0; n < 2; ++n) acc[a][b][m][n] = (f32x4){0.f, 0.f, 0.f, 0.f};
;     bf16x8 At[4][2], B0[2][2], B1[2][2];
;     const char* cA = S.abase(g, cur); const char* cB = S.bbase(g, cur);
;     S.a_ready(cur);
;     if constexpr (SP2) {
;         PG8_STAGE(PG8_SB(0, 0), cB, voffB); PG8_STAGE(PG8_SB(0, 1), cB + hstepB, voffB); PG8_STAGE(PG8_SA(0, 0), cA, voffA); PG8_STAGE(PG8_SA(0, 1), cA + hstepA, voffA);
;         if (wr == 1) PG8_BAR;
;         PG8_WAIT_V(2); PG8_BAR;
;         PG8_STAGE(PG8_SB(1, 0), cB + kstep, voffB); PG8_STAGE(PG8_SA(1, 0), cA + kstep, voffA); PG8_STAGE(PG8_SB(1, 1), cB + hstepB + kstep, voffB);
;         PG8_WAIT_V(6); PG8_BAR;
;     } else {
;         PG8_STAGE(PG8_SB(0, 0), cB, voffB); PG8_STAGE(PG8_SA(0, 0), cA, voffA); PG8_STAGE(PG8_SB(0, 1), cB + hstepB, voffB); PG8_STAGE(PG8_SA(0, 1), cA + hstepA, voffA);
;         if (wr == 1) PG8_BAR;
;         PG8_WAIT_V(4); PG8_BAR;
;         PG8_STAGE(PG8_SB(1, 0), cB + kstep, voffB); PG8_STAGE(PG8_SA(1, 0), cA + kstep, voffA); PG8_STAGE(PG8_SB(1, 1), cB + hstepB + kstep, voffB);
;         PG8_WAIT_V(6); PG8_BAR;
;     }
.LBB0_1069:
	s_lshl_b32 s12, s12, 5
	s_lshl_b32 s43, s13, 6
	s_lshl_b32 s16, s13, 13
	s_and_b32 s44, s12, 0x60
	s_mov_b64 s[12:13], 0x800
	s_add_i32 m0, s3, 0x18000
	v_lshl_add_u64 v[6:7], v[6:7], 0, s[12:13]
	s_lshl_b32 s17, s44, 7
	s_waitcnt vmcnt(2)
	s_barrier
	global_load_lds_dwordx4 v[6:7], off
	v_lshl_add_u64 v[4:5], v[4:5], 0, s[12:13]
	s_add_i32 m0, s3, 0x1a000
	s_add_i32 s45, s3, 0x8000
	s_add_i32 s46, s3, 0xa000
	global_load_lds_dwordx4 v[4:5], off
	v_lshl_add_u64 v[0:1], v[0:1], 0, s[12:13]
	s_mov_b32 m0, s45
	s_add_u32 s14, s24, 0x80800
	global_load_lds_dwordx4 v[0:1], off
	v_lshl_add_u64 v[0:1], v[2:3], 0, s[12:13]
	s_mov_b32 m0, s46
	s_addc_u32 s15, s25, 0
	global_load_lds_dwordx4 v[0:1], off
	s_add_i32 m0, s3, 0x1c000
	v_lshl_add_u64 v[0:1], s[14:15], 0, v[148:149]
	global_load_lds_dwordx4 v[0:1], off
	v_lshl_add_u64 v[0:1], s[14:15], 0, v[144:145]
	s_add_i32 m0, s3, 0x1e000
	v_bfe_u32 v163, v8, 4, 2
	global_load_lds_dwordx4 v[0:1], off
	v_and_b32_e32 v162, 15, v8
	v_lshlrev_b32_e32 v0, 4, v163
	v_lshlrev_b32_e32 v1, 2, v8
	v_lshl_or_b32 v0, v162, 6, v0
	v_and_b32_e32 v1, 32, v1
	v_bitop3_b32 v2, v0, s16, v1 bitop3:0xde
	v_bitop3_b32 v164, v0, s17, v1 bitop3:0xde
	v_lshlrev_b32_e32 v0, 14, v13
	v_and_b32_e32 v0, 0xffff8000, v0
	v_lshl_add_u32 v0, v12, 11, v0
	v_and_b32_e32 v1, 1, v13
	v_lshl_or_b32 v0, v1, 6, v0
	v_lshl_add_u32 v152, v14, 1, v0
	v_lshlrev_b32_e32 v0, 14, v9
	s_cmpk_lt_u32 s6, 0x100
	v_and_b32_e32 v0, 0xffff8000, v0
	s_waitcnt vmcnt(6)
	s_cselect_b64 s[14:15], -1, 0
	v_lshl_add_u32 v0, v10, 11, v0
	v_and_b32_e32 v1, 1, v9
	s_add_i32 s49, 0, 0x10000
	s_add_i32 s51, 0, 0x14000
	v_lshl_or_b32 v0, v1, 6, v0
	v_add_u32_e32 v165, s49, v164
	v_add_u32_e32 v166, s51, v164
	s_add_i32 s49, s49, s29
	s_add_i32 s51, s51, s29
	v_mov_b32_e32 v153, v149
	v_lshl_add_u32 v154, v11, 1, v0
	v_mov_b32_e32 v155, v149
	v_add_u32_e32 v167, 0, v2
	s_add_i32 s47, s3, 0xc000
	s_add_i32 s48, s3, 0xe000
	s_add_i32 s50, s49, 0x2000
	s_add_i32 s52, s51, 0x2000
	s_mov_b32 s55, s28
	s_mov_b32 s56, s2
	s_mov_b32 s53, 0
	s_barrier
	s_branch .LBB0_1072

;     __device__ __forceinline__ const char* abase(const Gemm& g, const Unit& u) const { return (const char*)g.A + (size_t)u.pm * ((size_t)BM * g.lda * 2); }
;     __device__ __forceinline__ const char* bbase(const Gemm& g, const Unit& u) const { return (const char*)g.Bt + (size_t)u.pn * ((size_t)BM * g.ldb * 2); }
; #define PG8_STAGE(bufoff, gbase, voff) do { _Pragma("unroll") for (int _i = 0; _i < 2; ++_i) \
;         __builtin_amdgcn_global_load_lds((const unsigned*)((const char*)(gbase) + (voff)[_i]), (PG8_LAS unsigned*)(lds + (bufoff) + ldsw + _i * 8192), 16, 0, 0); } while (0)
; #define PG8_LDA(dst, b, h) do { _Pragma("unroll") for (int m = 0; m < 4; ++m) _Pragma("unroll") for (int k = 0; k < 2; ++k) dst[m][k] = *(const PG8_LAS bf16x8*)(lds + PG8_SA(b, h) + aoff + m * 2048 + k * 1024); } while (0)
; #define PG8_WAIT_V(n) asm volatile("s_waitcnt vmcnt(" #n ")" ::: "memory")
; #define PG8_WAIT_L(n) asm volatile("s_waitcnt lgkmcnt(" #n ")" ::: "memory")
; #define PG8_BAR __builtin_amdgcn_s_barrier()
; template <class Epi, class Sched, bool ALIGN_EPI = false, bool SP2 = false>
; __device__ __forceinline__ void gemm_phase(PG8_LAS unsigned char* lds, const Gemm g, const Sched& S, const Epi& E, int wave_sgpr) {
;     ...
;     for (;;) {
;         const bool has_next = S.next(ui + 1, nxt);
;         const char* nA = has_next ? S.abase(g, nxt) : cA; const char* nB = has_next ? S.bbase(g, nxt) : cB;
;         for (int t = 0; t < nt; t += 2) {
;             const bool last = (t == nt - 2);
;             const char* a1 = cA + (size_t)(t + 1) * kstep;
;             const char* a2 = last ? nA : cA + (size_t)(t + 2) * kstep; const char* b2 = last ? nB : cB + (size_t)(t + 2) * kstep;
;             const char* a3 = a2 + kstep; const char* b3 = b2 + kstep;
;             if (last && has_next) S.a_ready(nxt);
;             if constexpr (SP2) {
;             PG8_LDB(B0, 0, 0); PG8_LDB(B1, 0, 1); PG8_SCHED; PG8_LDA(At, 0, 0); PG8_STAGE(PG8_SA(1, 1), a1 + hstepA, voffA);
;             PG8_WAIT_V(8); PG8_WAIT_L(0); PG8_BAR; PG8_MMA(0, 0, At, B0); PG8_MMA(0, 1, At, B1); PG8_BAR; PG8_SCHED;
;     ...
; #pragma unroll
;         for (int a = 0; a < 2; ++a)
; #pragma unroll
;             for (int b = 0; b < 2; ++b)
; #pragma unroll
;                 for (int m = 0; m < 4; ++m)
; #pragma unroll
;                     for (int n = 0; n < 2; ++n) acc[a][b][m][n] = (f32x4){0.f, 0.f, 0.f, 0.f};
.LBB0_1076:
	s_lshl_b64 s[20:21], s[20:21], 20
	s_add_u32 s20, s31, s20
	s_addc_u32 s21, s33, s21
	s_and_b64 s[26:27], exec, s[16:17]
	s_cselect_b32 s57, s21, s25
	s_cselect_b32 s58, s20, s24
	s_add_u32 s22, s22, 0x40800
	s_addc_u32 s23, s23, 0
	s_add_u32 s59, s24, 0x80
	v_mov_b32_e32 v0, 0
	s_addc_u32 s60, s25, 0
	s_mov_b32 s61, -2
	v_mov_b32_e32 v1, v0
	v_mov_b32_e32 v2, v0
	v_mov_b32_e32 v3, v0
	v_mov_b32_e32 v4, v0
	v_mov_b32_e32 v5, v0
	v_mov_b32_e32 v6, v0
	v_mov_b32_e32 v7, v0
	v_mov_b32_e32 v16, v0
	v_mov_b32_e32 v17, v0
	v_mov_b32_e32 v18, v0
	v_mov_b32_e32 v19, v0
	v_mov_b32_e32 v20, v0
	v_mov_b32_e32 v21, v0
	v_mov_b32_e32 v22, v0
	v_mov_b32_e32 v23, v0
	v_mov_b32_e32 v32, v0
	v_mov_b32_e32 v33, v0
	v_mov_b32_e32 v34, v0
	v_mov_b32_e32 v35, v0
	v_mov_b32_e32 v36, v0
	v_mov_b32_e32 v37, v0
	v_mov_b32_e32 v38, v0
	v_mov_b32_e32 v39, v0
	v_mov_b32_e32 v48, v0
	v_mov_b32_e32 v49, v0
	v_mov_b32_e32 v50, v0
	v_mov_b32_e32 v51, v0
	v_mov_b32_e32 v52, v0
	v_mov_b32_e32 v53, v0
	v_mov_b32_e32 v54, v0
	v_mov_b32_e32 v55, v0
	v_mov_b32_e32 v8, v0
	v_mov_b32_e32 v9, v0
	v_mov_b32_e32 v10, v0
	v_mov_b32_e32 v11, v0
	v_mov_b32_e32 v12, v0
	v_mov_b32_e32 v13, v0
	v_mov_b32_e32 v14, v0
	v_mov_b32_e32 v15, v0
	v_mov_b32_e32 v24, v0
	v_mov_b32_e32 v25, v0
	v_mov_b32_e32 v26, v0
	v_mov_b32_e32 v27, v0
	v_mov_b32_e32 v28, v0
	v_mov_b32_e32 v29, v0
	v_mov_b32_e32 v30, v0
	v_mov_b32_e32 v31, v0
	v_mov_b32_e32 v40, v0
	v_mov_b32_e32 v41, v0
	v_mov_b32_e32 v42, v0
	v_mov_b32_e32 v43, v0
	v_mov_b32_e32 v44, v0
	v_mov_b32_e32 v45, v0
	v_mov_b32_e32 v46, v0
	v_mov_b32_e32 v47, v0
	v_mov_b32_e32 v64, v0
	v_mov_b32_e32 v65, v0
	v_mov_b32_e32 v66, v0
	v_mov_b32_e32 v67, v0
	v_mov_b32_e32 v68, v0
	v_mov_b32_e32 v69, v0
	v_mov_b32_e32 v70, v0
	v_mov_b32_e32 v71, v0
	v_mov_b32_e32 v80, v0
	v_mov_b32_e32 v81, v0
	v_mov_b32_e32 v82, v0
	v_mov_b32_e32 v83, v0
	v_mov_b32_e32 v84, v0
	v_mov_b32_e32 v85, v0
	v_mov_b32_e32 v86, v0
	v_mov_b32_e32 v87, v0
	v_mov_b32_e32 v96, v0
	v_mov_b32_e32 v97, v0
	v_mov_b32_e32 v98, v0
	v_mov_b32_e32 v99, v0
	v_mov_b32_e32 v100, v0
	v_mov_b32_e32 v101, v0
	v_mov_b32_e32 v102, v0
	v_mov_b32_e32 v103, v0
	v_mov_b32_e32 v112, v0
	v_mov_b32_e32 v113, v0
	v_mov_b32_e32 v114, v0
	v_mov_b32_e32 v115, v0
	v_mov_b32_e32 v116, v0
	v_mov_b32_e32 v117, v0
	v_mov_b32_e32 v118, v0
	v_mov_b32_e32 v119, v0
	v_mov_b32_e32 v128, v0
	v_mov_b32_e32 v129, v0
	v_mov_b32_e32 v130, v0
	v_mov_b32_e32 v131, v0
	v_mov_b32_e32 v132, v0
	v_mov_b32_e32 v133, v0
	v_mov_b32_e32 v134, v0
	v_mov_b32_e32 v135, v0
	v_mov_b32_e32 v88, v0
	v_mov_b32_e32 v89, v0
	v_mov_b32_e32 v90, v0
	v_mov_b32_e32 v91, v0
	v_mov_b32_e32 v92, v0
	v_mov_b32_e32 v93, v0
	v_mov_b32_e32 v94, v0
	v_mov_b32_e32 v95, v0
	v_mov_b32_e32 v104, v0
	v_mov_b32_e32 v105, v0
	v_mov_b32_e32 v106, v0
	v_mov_b32_e32 v107, v0
	v_mov_b32_e32 v108, v0
	v_mov_b32_e32 v109, v0
	v_mov_b32_e32 v110, v0
	v_mov_b32_e32 v111, v0
	v_mov_b32_e32 v120, v0
	v_mov_b32_e32 v121, v0
	v_mov_b32_e32 v122, v0
	v_mov_b32_e32 v123, v0
	v_mov_b32_e32 v124, v0
	v_mov_b32_e32 v125, v0
	v_mov_b32_e32 v126, v0
	v_mov_b32_e32 v127, v0
	v_mov_b32_e32 v136, v0
	v_mov_b32_e32 v137, v0
	v_mov_b32_e32 v138, v0
	v_mov_b32_e32 v139, v0
	v_mov_b32_e32 v140, v0
	v_mov_b32_e32 v141, v0
	v_mov_b32_e32 v142, v0
	v_mov_b32_e32 v143, v0
.LBB0_1077:
	ds_read_b128 v[56:59], v165
	ds_read_b128 v[60:63], v165 offset:1024
	ds_read_b128 v[72:75], v165 offset:2048
	ds_read_b128 v[76:79], v165 offset:3072
	ds_read_b128 v[156:159], v166
	ds_read_b128 v[168:171], v166 offset:1024
	ds_read_b128 v[172:175], v166 offset:2048
	ds_read_b128 v[176:179], v166 offset:3072
	s_add_u32 s24, s22, 0xfffbf880
	s_addc_u32 s25, s23, -1
	s_cmp_eq_u32 s61, 28
	s_cselect_b32 s27, s19, s25
	s_cselect_b32 s26, s18, s24
	s_cselect_b32 s25, s57, s60
	s_cselect_b32 s24, s58, s59
	s_mov_b32 m0, s47
	v_lshl_add_u64 v[160:161], s[22:23], 0, v[152:153]
	ds_read_b128 v[180:183], v167
	ds_read_b128 v[184:187], v167 offset:1024
	ds_read_b128 v[188:191], v167 offset:2048
	ds_read_b128 v[192:195], v167 offset:3072
	ds_read_b128 v[196:199], v167 offset:4096
	ds_read_b128 v[200:203], v167 offset:5120
	ds_read_b128 v[204:207], v167 offset:6144
	ds_read_b128 v[208:211], v167 offset:7168
	global_load_lds_dwordx4 v[160:161], off
	v_lshl_add_u64 v[160:161], s[22:23], 0, v[154:155]
	s_mov_b32 m0, s48
	s_nop 0
	global_load_lds_dwordx4 v[160:161], off
	s_waitcnt vmcnt(8)
	s_waitcnt lgkmcnt(0)
	s_barrier
	s_setprio 1
	s_waitcnt lgkmcnt(0)
	v_mfma_f32_16x16x32_bf16 v[140:143], v[56:59], v[180:183], v[140:143]
	v_mfma_f32_16x16x32_bf16 v[136:139], v[72:75], v[180:183], v[136:139]
	v_mfma_f32_16x16x32_bf16 v[124:127], v[56:59], v[188:191], v[124:127]
	v_mfma_f32_16x16x32_bf16 v[120:123], v[72:75], v[188:191], v[120:123]
	v_mfma_f32_16x16x32_bf16 v[108:111], v[56:59], v[196:199], v[108:111]
	v_mfma_f32_16x16x32_bf16 v[104:107], v[72:75], v[196:199], v[104:107]
	v_mfma_f32_16x16x32_bf16 v[92:95], v[56:59], v[204:207], v[92:95]
	v_mfma_f32_16x16x32_bf16 v[88:91], v[72:75], v[204:207], v[88:91]
	v_mfma_f32_16x16x32_bf16 v[140:143], v[60:63], v[184:187], v[140:143]
	v_mfma_f32_16x16x32_bf16 v[136:139], v[76:79], v[184:187], v[136:139]
	v_mfma_f32_16x16x32_bf16 v[124:127], v[60:63], v[192:195], v[124:127]
	v_mfma_f32_16x16x32_bf16 v[120:123], v[76:79], v[192:195], v[120:123]
	v_mfma_f32_16x16x32_bf16 v[108:111], v[60:63], v[200:203], v[108:111]
	v_mfma_f32_16x16x32_bf16 v[104:107], v[76:79], v[200:203], v[104:107]
	v_mfma_f32_16x16x32_bf16 v[92:95], v[60:63], v[208:211], v[92:95]
	v_mfma_f32_16x16x32_bf16 v[88:91], v[76:79], v[208:211], v[88:91]
	s_setprio 0
	s_setprio 1
	v_mfma_f32_16x16x32_bf16 v[132:135], v[156:159], v[180:183], v[132:135]
	v_mfma_f32_16x16x32_bf16 v[128:131], v[172:175], v[180:183], v[128:131]
	v_mfma_f32_16x16x32_bf16 v[116:119], v[156:159], v[188:191], v[116:119]
	v_mfma_f32_16x16x32_bf16 v[112:115], v[172:175], v[188:191], v[112:115]
	v_mfma_f32_16x16x32_bf16 v[100:103], v[156:159], v[196:199], v[100:103]
	v_mfma_f32_16x16x32_bf16 v[96:99], v[172:175], v[196:199], v[96:99]
	v_mfma_f32_16x16x32_bf16 v[84:87], v[156:159], v[204:207], v[84:87]
	v_mfma_f32_16x16x32_bf16 v[80:83], v[172:175], v[204:207], v[80:83]
	v_mfma_f32_16x16x32_bf16 v[132:135], v[168:171], v[184:187], v[132:135]
	v_mfma_f32_16x16x32_bf16 v[128:131], v[176:179], v[184:187], v[128:131]
	v_mfma_f32_16x16x32_bf16 v[116:119], v[168:171], v[192:195], v[116:119]
	v_mfma_f32_16x16x32_bf16 v[112:115], v[176:179], v[192:195], v[112:115]
	v_mfma_f32_16x16x32_bf16 v[100:103], v[168:171], v[200:203], v[100:103]
	v_mfma_f32_16x16x32_bf16 v[96:99], v[176:179], v[200:203], v[96:99]
	v_mfma_f32_16x16x32_bf16 v[84:87], v[168:171], v[208:211], v[84:87]
	v_mfma_f32_16x16x32_bf16 v[80:83], v[176:179], v[208:211], v[80:83]
	s_setprio 0
	s_barrier
; #define PG8_STAGE(bufoff, gbase, voff) do { _Pragma("unroll") for (int _i = 0; _i < 2; ++_i) \
;         __builtin_amdgcn_global_load_lds((const unsigned*)((const char*)(gbase) + (voff)[_i]), (PG8_LAS unsigned*)(lds + (bufoff) + ldsw + _i * 8192), 16, 0, 0); } while (0)
; #define PG8_LDA(dst, b, h) do { _Pragma("unroll") for (int m = 0; m < 4; ++m) _Pragma("unroll") for (int k = 0; k < 2; ++k) dst[m][k] = *(const PG8_LAS bf16x8*)(lds + PG8_SA(b, h) + aoff + m * 2048 + k * 1024); } while (0)
; #define PG8_LDB(dst, b, h) do { _Pragma("unroll") for (int n = 0; n < 2; ++n) _Pragma("unroll") for (int k = 0; k < 2; ++k) dst[n][k] = *(const PG8_LAS bf16x8*)(lds + PG8_SB(b, h) + boff + n * 2048 + k * 1024); } while (0)
; #define PG8_MMA(ai, bj, At, Bt) do { __builtin_amdgcn_s_setprio(1); _Pragma("unroll") for (int m = 0; m < 4; ++m) _Pragma("unroll") for (int n = 0; n < 2; ++n) _Pragma("unroll") for (int k = 0; k < 2; ++k) \
;         acc[ai][bj][m][n] = __builtin_amdgcn_mfma_f32_16x16x32_bf16(Bt[n][k], At[m][k], acc[ai][bj][m][n], 0, 0, 0); __builtin_amdgcn_s_setprio(0); } while (0)
; #define PG8_WAIT_V(n) asm volatile("s_waitcnt vmcnt(" #n ")" ::: "memory")
; #define PG8_WAIT_L(n) asm volatile("s_waitcnt lgkmcnt(" #n ")" ::: "memory")
; #define PG8_BAR __builtin_amdgcn_s_barrier()
; #define PG8_SCHED __builtin_amdgcn_sched_barrier(0)
; template <class Epi, class Sched, bool ALIGN_EPI = false, bool SP2 = false>
; __device__ __forceinline__ void gemm_phase(PG8_LAS unsigned char* lds, const Gemm g, const Sched& S, const Epi& E, int wave_sgpr) {
;     ...
;             PG8_LDA(At, 0, 1); PG8_STAGE(PG8_SB(0, 0), b2, voffB); PG8_STAGE(PG8_SB(0, 1), b2 + hstepB, voffB); PG8_STAGE(PG8_SA(0, 0), a2, voffA);
;             PG8_WAIT_V(8); PG8_WAIT_L(0); PG8_BAR; PG8_MMA(1, 0, At, B0); PG8_MMA(1, 1, At, B1); PG8_BAR; PG8_SCHED;
;             PG8_LDB(B0, 1, 0); PG8_LDB(B1, 1, 1); PG8_SCHED; PG8_LDA(At, 1, 0); PG8_STAGE(PG8_SA(0, 1), a2 + hstepA, voffA);
;             PG8_WAIT_V(8); PG8_WAIT_L(0); PG8_BAR; PG8_MMA(0, 0, At, B0); PG8_MMA(0, 1, At, B1); PG8_BAR; PG8_SCHED;
	s_mov_b32 m0, s49
	v_lshl_add_u64 v[160:161], s[24:25], 0, v[148:149]
	s_add_u32 s62, s24, 0x80000
	ds_read_b128 v[180:183], v167 offset:16384
	ds_read_b128 v[184:187], v167 offset:17408
	ds_read_b128 v[188:191], v167 offset:18432
	ds_read_b128 v[192:195], v167 offset:19456
	ds_read_b128 v[196:199], v167 offset:20480
	ds_read_b128 v[200:203], v167 offset:21504
	ds_read_b128 v[204:207], v167 offset:22528
	ds_read_b128 v[208:211], v167 offset:23552
	global_load_lds_dwordx4 v[160:161], off
	v_lshl_add_u64 v[212:213], s[24:25], 0, v[144:145]
	s_mov_b32 m0, s50
	s_addc_u32 s63, s25, 0
	global_load_lds_dwordx4 v[212:213], off
	v_lshl_add_u64 v[214:215], s[62:63], 0, v[148:149]
	s_mov_b32 m0, s51
	v_lshl_add_u64 v[216:217], s[26:27], 0, v[146:147]
	global_load_lds_dwordx4 v[214:215], off
	v_lshl_add_u64 v[214:215], s[62:63], 0, v[144:145]
	s_mov_b32 m0, s52
	s_nop 0
	global_load_lds_dwordx4 v[214:215], off
	v_lshl_add_u64 v[214:215], s[26:27], 0, v[150:151]
	s_mov_b32 m0, s3
	s_nop 0
	global_load_lds_dwordx4 v[214:215], off
	s_mov_b32 m0, s40
	s_nop 0
	global_load_lds_dwordx4 v[216:217], off
	s_waitcnt vmcnt(8)
	s_waitcnt lgkmcnt(0)
	s_barrier
	s_setprio 1
	s_waitcnt lgkmcnt(0)
	v_mfma_f32_16x16x32_bf16 v[68:71], v[56:59], v[180:183], v[68:71]
	v_mfma_f32_16x16x32_bf16 v[64:67], v[72:75], v[180:183], v[64:67]
	v_mfma_f32_16x16x32_bf16 v[44:47], v[56:59], v[188:191], v[44:47]
	v_mfma_f32_16x16x32_bf16 v[40:43], v[72:75], v[188:191], v[40:43]
	v_mfma_f32_16x16x32_bf16 v[28:31], v[56:59], v[196:199], v[28:31]
	v_mfma_f32_16x16x32_bf16 v[24:27], v[72:75], v[196:199], v[24:27]
	v_mfma_f32_16x16x32_bf16 v[12:15], v[56:59], v[204:207], v[12:15]
	v_mfma_f32_16x16x32_bf16 v[8:11], v[72:75], v[204:207], v[8:11]
	v_mfma_f32_16x16x32_bf16 v[68:71], v[60:63], v[184:187], v[68:71]
	v_mfma_f32_16x16x32_bf16 v[64:67], v[76:79], v[184:187], v[64:67]
	v_mfma_f32_16x16x32_bf16 v[44:47], v[60:63], v[192:195], v[44:47]
	v_mfma_f32_16x16x32_bf16 v[40:43], v[76:79], v[192:195], v[40:43]
	v_mfma_f32_16x16x32_bf16 v[28:31], v[60:63], v[200:203], v[28:31]
	v_mfma_f32_16x16x32_bf16 v[24:27], v[76:79], v[200:203], v[24:27]
	v_mfma_f32_16x16x32_bf16 v[12:15], v[60:63], v[208:211], v[12:15]
	v_mfma_f32_16x16x32_bf16 v[8:11], v[76:79], v[208:211], v[8:11]
	s_setprio 0
	s_setprio 1
	v_mfma_f32_16x16x32_bf16 v[52:55], v[156:159], v[180:183], v[52:55]
	v_mfma_f32_16x16x32_bf16 v[48:51], v[172:175], v[180:183], v[48:51]
	v_mfma_f32_16x16x32_bf16 v[36:39], v[156:159], v[188:191], v[36:39]
	v_mfma_f32_16x16x32_bf16 v[32:35], v[172:175], v[188:191], v[32:35]
	v_mfma_f32_16x16x32_bf16 v[20:23], v[156:159], v[196:199], v[20:23]
	v_mfma_f32_16x16x32_bf16 v[16:19], v[172:175], v[196:199], v[16:19]
	v_mfma_f32_16x16x32_bf16 v[4:7], v[156:159], v[204:207], v[4:7]
	v_mfma_f32_16x16x32_bf16 v[0:3], v[172:175], v[204:207], v[0:3]
	v_mfma_f32_16x16x32_bf16 v[52:55], v[168:171], v[184:187], v[52:55]
	v_mfma_f32_16x16x32_bf16 v[48:51], v[176:179], v[184:187], v[48:51]
	v_mfma_f32_16x16x32_bf16 v[36:39], v[168:171], v[192:195], v[36:39]
	v_mfma_f32_16x16x32_bf16 v[32:35], v[176:179], v[192:195], v[32:35]
	v_mfma_f32_16x16x32_bf16 v[20:23], v[168:171], v[200:203], v[20:23]
	v_mfma_f32_16x16x32_bf16 v[16:19], v[176:179], v[200:203], v[16:19]
	v_mfma_f32_16x16x32_bf16 v[4:7], v[168:171], v[208:211], v[4:7]
	v_mfma_f32_16x16x32_bf16 v[0:3], v[176:179], v[208:211], v[0:3]
	s_setprio 0
	s_barrier
	s_add_i32 s62, 0, 0x18000
	s_add_i32 s63, 0, 0x1c000
	v_add_u32_e32 v76, s62, v164
	v_add_u32_e32 v176, s63, v164
	ds_read_b128 v[56:59], v76
	ds_read_b128 v[60:63], v76 offset:1024
	ds_read_b128 v[72:75], v76 offset:2048
	ds_read_b128 v[76:79], v76 offset:3072
	ds_read_b128 v[156:159], v176
	ds_read_b128 v[168:171], v176 offset:1024
	ds_read_b128 v[172:175], v176 offset:2048
	ds_read_b128 v[176:179], v176 offset:3072
	s_add_u32 s26, s26, 0x40000
	s_addc_u32 s27, s27, 0
	s_mov_b32 m0, s41
	v_lshl_add_u64 v[218:219], s[26:27], 0, v[150:151]
	ds_read_b128 v[180:183], v167 offset:32768
	ds_read_b128 v[184:187], v167 offset:33792
	ds_read_b128 v[188:191], v167 offset:34816
	ds_read_b128 v[192:195], v167 offset:35840
	ds_read_b128 v[196:199], v167 offset:36864
	ds_read_b128 v[200:203], v167 offset:37888
	ds_read_b128 v[204:207], v167 offset:38912
	ds_read_b128 v[208:211], v167 offset:39936
	global_load_lds_dwordx4 v[218:219], off
	v_lshl_add_u64 v[218:219], s[26:27], 0, v[146:147]
	s_mov_b32 m0, s42
	s_nop 0
	global_load_lds_dwordx4 v[218:219], off
	s_waitcnt vmcnt(8)
	s_waitcnt lgkmcnt(0)
	s_barrier
; #define PG8_STAGE(bufoff, gbase, voff) do { _Pragma("unroll") for (int _i = 0; _i < 2; ++_i) \
;         __builtin_amdgcn_global_load_lds((const unsigned*)((const char*)(gbase) + (voff)[_i]), (PG8_LAS unsigned*)(lds + (bufoff) + ldsw + _i * 8192), 16, 0, 0); } while (0)
; #define PG8_LDA(dst, b, h) do { _Pragma("unroll") for (int m = 0; m < 4; ++m) _Pragma("unroll") for (int k = 0; k < 2; ++k) dst[m][k] = *(const PG8_LAS bf16x8*)(lds + PG8_SA(b, h) + aoff + m * 2048 + k * 1024); } while (0)
; #define PG8_LDB(dst, b, h) do { _Pragma("unroll") for (int n = 0; n < 2; ++n) _Pragma("unroll") for (int k = 0; k < 2; ++k) dst[n][k] = *(const PG8_LAS bf16x8*)(lds + PG8_SB(b, h) + boff + n * 2048 + k * 1024); } while (0)
; #define PG8_MMA(ai, bj, At, Bt) do { __builtin_amdgcn_s_setprio(1); _Pragma("unroll") for (int m = 0; m < 4; ++m) _Pragma("unroll") for (int n = 0; n < 2; ++n) _Pragma("unroll") for (int k = 0; k < 2; ++k) \
;         acc[ai][bj][m][n] = __builtin_amdgcn_mfma_f32_16x16x32_bf16(Bt[n][k], At[m][k], acc[ai][bj][m][n], 0, 0, 0); __builtin_amdgcn_s_setprio(0); } while (0)
; #define PG8_WAIT_V(n) asm volatile("s_waitcnt vmcnt(" #n ")" ::: "memory")
; #define PG8_WAIT_L(n) asm volatile("s_waitcnt lgkmcnt(" #n ")" ::: "memory")
; #define PG8_BAR __builtin_amdgcn_s_barrier()
; #define PG8_SCHED __builtin_amdgcn_sched_barrier(0)
; template <class Epi, class Sched, bool ALIGN_EPI = false, bool SP2 = false>
; __device__ __forceinline__ void gemm_phase(PG8_LAS unsigned char* lds, const Gemm g, const Sched& S, const Epi& E, int wave_sgpr) {
;     ...
;             PG8_LDB(B0, 1, 0); PG8_LDB(B1, 1, 1); PG8_SCHED; PG8_LDA(At, 1, 0); PG8_STAGE(PG8_SA(0, 1), a2 + hstepA, voffA);
;             PG8_WAIT_V(8); PG8_WAIT_L(0); PG8_BAR; PG8_MMA(0, 0, At, B0); PG8_MMA(0, 1, At, B1); PG8_BAR; PG8_SCHED;
;             PG8_LDA(At, 1, 1); PG8_STAGE(PG8_SB(1, 0), b3, voffB); PG8_STAGE(PG8_SB(1, 1), b3 + hstepB, voffB); PG8_STAGE(PG8_SA(1, 0), a3, voffA);
;             PG8_WAIT_V(8); PG8_WAIT_L(0); PG8_BAR; PG8_MMA(1, 0, At, B0); PG8_MMA(1, 1, At, B1); PG8_BAR; PG8_SCHED;
	s_setprio 1
	s_waitcnt lgkmcnt(0)
	v_mfma_f32_16x16x32_bf16 v[140:143], v[56:59], v[180:183], v[140:143]
	v_mfma_f32_16x16x32_bf16 v[136:139], v[72:75], v[180:183], v[136:139]
	v_mfma_f32_16x16x32_bf16 v[124:127], v[56:59], v[188:191], v[124:127]
	v_mfma_f32_16x16x32_bf16 v[120:123], v[72:75], v[188:191], v[120:123]
	v_mfma_f32_16x16x32_bf16 v[108:111], v[56:59], v[196:199], v[108:111]
	v_mfma_f32_16x16x32_bf16 v[104:107], v[72:75], v[196:199], v[104:107]
	v_mfma_f32_16x16x32_bf16 v[92:95], v[56:59], v[204:207], v[92:95]
	v_mfma_f32_16x16x32_bf16 v[88:91], v[72:75], v[204:207], v[88:91]
	v_mfma_f32_16x16x32_bf16 v[140:143], v[60:63], v[184:187], v[140:143]
	v_mfma_f32_16x16x32_bf16 v[136:139], v[76:79], v[184:187], v[136:139]
	v_mfma_f32_16x16x32_bf16 v[124:127], v[60:63], v[192:195], v[124:127]
	v_mfma_f32_16x16x32_bf16 v[120:123], v[76:79], v[192:195], v[120:123]
	v_mfma_f32_16x16x32_bf16 v[108:111], v[60:63], v[200:203], v[108:111]
	v_mfma_f32_16x16x32_bf16 v[104:107], v[76:79], v[200:203], v[104:107]
	v_mfma_f32_16x16x32_bf16 v[92:95], v[60:63], v[208:211], v[92:95]
	v_mfma_f32_16x16x32_bf16 v[88:91], v[76:79], v[208:211], v[88:91]
	s_setprio 0
	s_setprio 1
	v_mfma_f32_16x16x32_bf16 v[132:135], v[156:159], v[180:183], v[132:135]
	v_mfma_f32_16x16x32_bf16 v[128:131], v[172:175], v[180:183], v[128:131]
	v_mfma_f32_16x16x32_bf16 v[116:119], v[156:159], v[188:191], v[116:119]
	v_mfma_f32_16x16x32_bf16 v[112:115], v[172:175], v[188:191], v[112:115]
	v_mfma_f32_16x16x32_bf16 v[100:103], v[156:159], v[196:199], v[100:103]
	v_mfma_f32_16x16x32_bf16 v[96:99], v[172:175], v[196:199], v[96:99]
	v_mfma_f32_16x16x32_bf16 v[84:87], v[156:159], v[204:207], v[84:87]
	v_mfma_f32_16x16x32_bf16 v[80:83], v[172:175], v[204:207], v[80:83]
	v_mfma_f32_16x16x32_bf16 v[132:135], v[168:171], v[184:187], v[132:135]
	v_mfma_f32_16x16x32_bf16 v[128:131], v[176:179], v[184:187], v[128:131]
	v_mfma_f32_16x16x32_bf16 v[116:119], v[168:171], v[192:195], v[116:119]
	v_mfma_f32_16x16x32_bf16 v[112:115], v[176:179], v[192:195], v[112:115]
	v_mfma_f32_16x16x32_bf16 v[100:103], v[168:171], v[200:203], v[100:103]
	v_mfma_f32_16x16x32_bf16 v[96:99], v[176:179], v[200:203], v[96:99]
	v_mfma_f32_16x16x32_bf16 v[84:87], v[168:171], v[208:211], v[84:87]
	v_mfma_f32_16x16x32_bf16 v[80:83], v[176:179], v[208:211], v[80:83]
	s_setprio 0
	s_barrier
	s_add_i32 s26, s62, s29
	v_lshl_add_u64 v[160:161], v[160:161], 0, s[12:13]
	s_mov_b32 m0, s26
	ds_read_b128 v[180:183], v167 offset:49152
	ds_read_b128 v[184:187], v167 offset:50176
	ds_read_b128 v[188:191], v167 offset:51200
	ds_read_b128 v[192:195], v167 offset:52224
	ds_read_b128 v[196:199], v167 offset:53248
	ds_read_b128 v[200:203], v167 offset:54272
	ds_read_b128 v[204:207], v167 offset:55296
	ds_read_b128 v[208:211], v167 offset:56320
	global_load_lds_dwordx4 v[160:161], off
	s_add_i32 m0, s26, 0x2000
	s_add_u32 s24, s24, 0x80800
	v_lshl_add_u64 v[160:161], v[212:213], 0, s[12:13]
	s_addc_u32 s25, s25, 0
	s_add_i32 s26, s63, s29
	global_load_lds_dwordx4 v[160:161], off
	v_lshl_add_u64 v[160:161], s[24:25], 0, v[148:149]
	s_mov_b32 m0, s26
	s_nop 0
	global_load_lds_dwordx4 v[160:161], off
	v_lshl_add_u64 v[160:161], s[24:25], 0, v[144:145]
	s_add_i32 m0, s26, 0x2000
	s_nop 0
	global_load_lds_dwordx4 v[160:161], off
	v_lshl_add_u64 v[160:161], v[214:215], 0, s[12:13]
	s_mov_b32 m0, s45
	s_nop 0
	global_load_lds_dwordx4 v[160:161], off
	v_lshl_add_u64 v[160:161], v[216:217], 0, s[12:13]
	s_mov_b32 m0, s46
	s_nop 0
	global_load_lds_dwordx4 v[160:161], off
	s_waitcnt vmcnt(8)
	s_waitcnt lgkmcnt(0)
	s_barrier
	s_setprio 1
	s_waitcnt lgkmcnt(0)
	v_mfma_f32_16x16x32_bf16 v[68:71], v[56:59], v[180:183], v[68:71]
	v_mfma_f32_16x16x32_bf16 v[64:67], v[72:75], v[180:183], v[64:67]
	v_mfma_f32_16x16x32_bf16 v[44:47], v[56:59], v[188:191], v[44:47]
	v_mfma_f32_16x16x32_bf16 v[40:43], v[72:75], v[188:191], v[40:43]
	v_mfma_f32_16x16x32_bf16 v[28:31], v[56:59], v[196:199], v[28:31]
	v_mfma_f32_16x16x32_bf16 v[24:27], v[72:75], v[196:199], v[24:27]
	v_mfma_f32_16x16x32_bf16 v[12:15], v[56:59], v[204:207], v[12:15]
	v_mfma_f32_16x16x32_bf16 v[8:11], v[72:75], v[204:207], v[8:11]
	v_mfma_f32_16x16x32_bf16 v[68:71], v[60:63], v[184:187], v[68:71]
	v_mfma_f32_16x16x32_bf16 v[64:67], v[76:79], v[184:187], v[64:67]
	v_mfma_f32_16x16x32_bf16 v[44:47], v[60:63], v[192:195], v[44:47]
	v_mfma_f32_16x16x32_bf16 v[40:43], v[76:79], v[192:195], v[40:43]
	v_mfma_f32_16x16x32_bf16 v[28:31], v[60:63], v[200:203], v[28:31]
	v_mfma_f32_16x16x32_bf16 v[24:27], v[76:79], v[200:203], v[24:27]
	v_mfma_f32_16x16x32_bf16 v[12:15], v[60:63], v[208:211], v[12:15]
	v_mfma_f32_16x16x32_bf16 v[8:11], v[76:79], v[208:211], v[8:11]
	s_setprio 0
	s_setprio 1
	v_mfma_f32_16x16x32_bf16 v[52:55], v[156:159], v[180:183], v[52:55]
	v_mfma_f32_16x16x32_bf16 v[48:51], v[172:175], v[180:183], v[48:51]
	v_mfma_f32_16x16x32_bf16 v[36:39], v[156:159], v[188:191], v[36:39]
	v_mfma_f32_16x16x32_bf16 v[32:35], v[172:175], v[188:191], v[32:35]
	v_mfma_f32_16x16x32_bf16 v[20:23], v[156:159], v[196:199], v[20:23]
	v_mfma_f32_16x16x32_bf16 v[16:19], v[172:175], v[196:199], v[16:19]
	v_mfma_f32_16x16x32_bf16 v[4:7], v[156:159], v[204:207], v[4:7]
	v_mfma_f32_16x16x32_bf16 v[0:3], v[172:175], v[204:207], v[0:3]
	v_mfma_f32_16x16x32_bf16 v[52:55], v[168:171], v[184:187], v[52:55]
	v_mfma_f32_16x16x32_bf16 v[48:51], v[176:179], v[184:187], v[48:51]
	v_mfma_f32_16x16x32_bf16 v[36:39], v[168:171], v[192:195], v[36:39]
	v_mfma_f32_16x16x32_bf16 v[32:35], v[176:179], v[192:195], v[32:35]
	v_mfma_f32_16x16x32_bf16 v[20:23], v[168:171], v[200:203], v[20:23]
	v_mfma_f32_16x16x32_bf16 v[16:19], v[176:179], v[200:203], v[16:19]
	v_mfma_f32_16x16x32_bf16 v[4:7], v[168:171], v[208:211], v[4:7]
	v_mfma_f32_16x16x32_bf16 v[0:3], v[176:179], v[208:211], v[0:3]
	s_setprio 0
	s_barrier
	s_add_i32 s61, s61, 2
	s_add_u32 s22, s22, 0x80
	s_addc_u32 s23, s23, 0
	s_add_u32 s59, s59, 0x80
	s_addc_u32 s60, s60, 0
	s_cmp_gt_u32 s61, 29
	s_cbranch_scc0 .LBB0_1077
	s_and_b64 vcc, exec, s[14:15]
	s_cbranch_vccz .LBB0_1080
	s_barrier
